# skinny residual GEMM epilogue: the lane's four residual inputs fetched together before the first store (no load behind a store/atomic)
# baseline (speedup 1.0000x reference)
; __device__ __forceinline__ unsigned f2bf(float f) { unsigned u = __builtin_bit_cast(unsigned, f); return (u + 0x7fffu + ((u >> 16) & 1u)) >> 16; }
; __device__ __forceinline__ void skinny_resid(const KA& A, const float* xin32  , LAS unsigned char* lds, int G, int bx, int wave, int lane, const bf16* Ain, int K, const bf16* Wt, bf16* xb, float* rowss_next, float alpha) {
;     ...
;             for (int i = 0; i < 4; ++i) { const int row = MP + 64 * rg + 16 * rf + 4 * fq + i; const size_t o = (size_t)row * 1024 + c0 + fr;
;                 const float v = (xin32 ? xin32[o] : bf2f(xb[o])) + alpha * acc[0][i]; xb[o] = (bf16)f2bf(v);
;                 float ss = v * v; ss += __shfl_xor(ss, 1); ss += __shfl_xor(ss, 2); ss += __shfl_xor(ss, 4); ss += __shfl_xor(ss, 8);
;                 if (fr == 0) __hip_atomic_fetch_add(rowss_next + row, ss, __ATOMIC_RELAXED, __HIP_MEMORY_SCOPE_AGENT); } } }
.LBB0_598:
	s_andn2_b64 vcc, exec, s[48:49]
	s_barrier
	s_cbranch_vccnz .LBB0_591
	v_or_b32_e32 v18, s42, v17
	v_mov_b32_e32 v13, s5
	v_or_b32_e32 v12, s4, v0
	v_lshlrev_b32_e32 v2, 10, v18
	v_cndmask_b32_e64 v14, 0, 1, s[50:51]
	v_cmp_ne_u32_e64 s[42:43], 1, v14
	s_andn2_b64 vcc, exec, s[50:51]
	v_lshl_add_u64 v[14:15], v[2:3], 0, v[12:13]
	v_mov_b32_e32 v71, 0
	v_mov_b32_e32 v73, 0
	v_mov_b32_e32 v75, 0
	v_or_b32_e32 v70, 1, v18
	v_or_b32_e32 v72, 2, v18
	v_or_b32_e32 v74, 3, v18
	v_lshlrev_b32_e32 v70, 10, v70
	v_lshlrev_b32_e32 v72, 10, v72
	v_lshlrev_b32_e32 v74, 10, v74
	v_lshl_add_u64 v[70:71], v[70:71], 0, v[12:13]
	v_lshl_add_u64 v[72:73], v[72:73], 0, v[12:13]
	v_lshl_add_u64 v[74:75], v[74:75], 0, v[12:13]
	s_cbranch_vccnz .Lsr_xb
	v_lshl_add_u64 v[76:77], v[14:15], 2, s[8:9]
	v_lshl_add_u64 v[70:71], v[70:71], 2, s[8:9]
	v_lshl_add_u64 v[72:73], v[72:73], 2, s[8:9]
	v_lshl_add_u64 v[74:75], v[74:75], 2, s[8:9]
	global_load_dword v78, v[76:77], off
	global_load_dword v79, v[70:71], off
	global_load_dword v80, v[72:73], off
	global_load_dword v81, v[74:75], off
	s_waitcnt vmcnt(0)
	s_branch .Lsr_go
.Lsr_xb:
	v_lshl_add_u64 v[76:77], v[14:15], 1, s[94:95]
	v_lshl_add_u64 v[70:71], v[70:71], 1, s[94:95]
	v_lshl_add_u64 v[72:73], v[72:73], 1, s[94:95]
	v_lshl_add_u64 v[74:75], v[74:75], 1, s[94:95]
	global_load_ushort v78, v[76:77], off
	global_load_ushort v79, v[70:71], off
	global_load_ushort v80, v[72:73], off
	global_load_ushort v81, v[74:75], off
	s_waitcnt vmcnt(0)
	v_lshlrev_b32_e32 v78, 16, v78
	v_lshlrev_b32_e32 v79, 16, v79
	v_lshlrev_b32_e32 v80, 16, v80
	v_lshlrev_b32_e32 v81, 16, v81
.Lsr_go:
	s_cbranch_vccnz .LBB0_619
	v_lshl_add_u64 v[20:21], v[14:15], 2, s[8:9]
	v_mov_b32_e32 v2, v78
	v_lshl_add_u64 v[14:15], v[14:15], 1, s[94:95]
	s_cbranch_execnz .LBB0_602
.LBB0_601:
	v_mov_b32_e32 v2, v78
.LBB0_602:
	v_and_b32_e32 v20, 64, v219
	v_xor_b32_e32 v19, 1, v219
	v_add_u32_e32 v22, 64, v20
	v_fmac_f32_e32 v2, v1, v4
	v_cmp_lt_i32_e32 vcc, v19, v22
	v_bfe_u32 v4, v2, 16, 1
	v_add3_u32 v4, v2, v4, s74
	v_cndmask_b32_e32 v19, v219, v19, vcc
	v_lshlrev_b32_e32 v19, 2, v19
	global_store_short_d16_hi v[14:15], v4, off
	v_mul_f32_e32 v4, v2, v2
	ds_bpermute_b32 v4, v19, v4
	v_xor_b32_e32 v20, 2, v219
	v_cmp_lt_i32_e32 vcc, v20, v22
	v_xor_b32_e32 v21, 4, v219
	v_xor_b32_e32 v23, 8, v219
	v_cndmask_b32_e32 v20, v219, v20, vcc
	v_lshlrev_b32_e32 v20, 2, v20
	s_waitcnt lgkmcnt(0)
	v_fmac_f32_e32 v4, v2, v2
	ds_bpermute_b32 v2, v20, v4
	v_cmp_lt_i32_e32 vcc, v21, v22
	s_waitcnt lgkmcnt(0)
	v_add_f32_e32 v2, v4, v2
	v_cndmask_b32_e32 v21, v219, v21, vcc
	v_lshlrev_b32_e32 v21, 2, v21
	ds_bpermute_b32 v4, v21, v2
	v_cmp_lt_i32_e32 vcc, v23, v22
	s_waitcnt lgkmcnt(0)
	v_add_f32_e32 v2, v2, v4
	v_cndmask_b32_e32 v22, v219, v23, vcc
	v_lshlrev_b32_e32 v22, 2, v22
	ds_bpermute_b32 v4, v22, v2
	s_and_saveexec_b64 s[4:5], s[40:41]
	s_cbranch_execz .LBB0_604
	s_waitcnt lgkmcnt(0)
	v_add_f32_e32 v2, v2, v4
	v_lshlrev_b32_e32 v4, 2, v18
	global_atomic_add_f32 v4, v2, s[44:45]
.LBB0_604:
	s_or_b64 exec, exec, s[4:5]
	s_waitcnt lgkmcnt(0)
	v_or_b32_e32 v4, 1, v18
	v_lshlrev_b32_e32 v2, 10, v4
	s_and_b64 vcc, exec, s[42:43]
	v_lshl_add_u64 v[14:15], v[2:3], 0, v[12:13]
	s_cbranch_vccnz .LBB0_620
	v_lshl_add_u64 v[24:25], v[14:15], 2, s[8:9]
	v_mov_b32_e32 v2, v79
	v_lshl_add_u64 v[14:15], v[14:15], 1, s[94:95]
	s_cbranch_execnz .LBB0_607
.LBB0_606:
	v_mov_b32_e32 v2, v79
.LBB0_607:
	v_fmac_f32_e32 v2, v1, v5
	v_bfe_u32 v5, v2, 16, 1
	v_add3_u32 v5, v2, v5, s74
	global_store_short_d16_hi v[14:15], v5, off
	v_mul_f32_e32 v5, v2, v2
	ds_bpermute_b32 v5, v19, v5
	s_waitcnt lgkmcnt(0)
	v_fmac_f32_e32 v5, v2, v2
	ds_bpermute_b32 v2, v20, v5
	s_waitcnt lgkmcnt(0)
	v_add_f32_e32 v2, v5, v2
	ds_bpermute_b32 v5, v21, v2
	s_waitcnt lgkmcnt(0)
	v_add_f32_e32 v2, v2, v5
	ds_bpermute_b32 v5, v22, v2
	s_and_saveexec_b64 s[4:5], s[40:41]
	s_cbranch_execz .LBB0_609
	s_waitcnt lgkmcnt(0)
	v_add_f32_e32 v2, v2, v5
	v_lshlrev_b32_e32 v4, 2, v4
	global_atomic_add_f32 v4, v2, s[44:45]
.LBB0_609:
	s_or_b64 exec, exec, s[4:5]
	v_or_b32_e32 v14, 2, v18
	v_lshlrev_b32_e32 v2, 10, v14
	s_and_b64 vcc, exec, s[42:43]
	s_waitcnt lgkmcnt(0)
	v_lshl_add_u64 v[4:5], v[2:3], 0, v[12:13]
	s_cbranch_vccnz .LBB0_621
	v_lshl_add_u64 v[24:25], v[4:5], 2, s[8:9]
	v_mov_b32_e32 v2, v80
	v_lshl_add_u64 v[4:5], v[4:5], 1, s[94:95]
	s_cbranch_execnz .LBB0_612
.LBB0_611:
	v_mov_b32_e32 v2, v80
.LBB0_612:
	v_fmac_f32_e32 v2, v1, v6
	v_bfe_u32 v6, v2, 16, 1
	v_add3_u32 v6, v2, v6, s74
	global_store_short_d16_hi v[4:5], v6, off
	v_mul_f32_e32 v4, v2, v2
	ds_bpermute_b32 v4, v19, v4
	s_waitcnt lgkmcnt(0)
	v_fmac_f32_e32 v4, v2, v2
	ds_bpermute_b32 v2, v20, v4
	s_waitcnt lgkmcnt(0)
	v_add_f32_e32 v2, v4, v2
	ds_bpermute_b32 v4, v21, v2
	s_waitcnt lgkmcnt(0)
	v_add_f32_e32 v2, v2, v4
	ds_bpermute_b32 v4, v22, v2
	s_and_saveexec_b64 s[4:5], s[40:41]
	s_cbranch_execz .LBB0_614
	s_waitcnt lgkmcnt(0)
	v_add_f32_e32 v2, v2, v4
	v_lshlrev_b32_e32 v4, 2, v14
	global_atomic_add_f32 v4, v2, s[44:45]
.LBB0_614:
	s_or_b64 exec, exec, s[4:5]
	v_or_b32_e32 v6, 3, v18
	v_lshlrev_b32_e32 v2, 10, v6
	s_and_b64 vcc, exec, s[42:43]
	s_waitcnt lgkmcnt(0)
	v_lshl_add_u64 v[4:5], v[2:3], 0, v[12:13]
	s_cbranch_vccnz .LBB0_622
	v_lshl_add_u64 v[12:13], v[4:5], 2, s[8:9]
	v_mov_b32_e32 v2, v81
	v_lshl_add_u64 v[4:5], v[4:5], 1, s[94:95]
	s_cbranch_execnz .LBB0_617
.LBB0_616:
	v_mov_b32_e32 v2, v81
.LBB0_617:
	v_fmac_f32_e32 v2, v1, v7
	v_mul_f32_e32 v7, v2, v2
	ds_bpermute_b32 v7, v19, v7
	v_bfe_u32 v13, v2, 16, 1
	s_waitcnt lgkmcnt(0)
	v_fmac_f32_e32 v7, v2, v2
	ds_bpermute_b32 v12, v20, v7
	v_add3_u32 v2, v2, v13, s74
	global_store_short_d16_hi v[4:5], v2, off
	s_waitcnt lgkmcnt(0)
	v_add_f32_e32 v7, v7, v12
	ds_bpermute_b32 v12, v21, v7
	s_waitcnt lgkmcnt(0)
	v_add_f32_e32 v7, v7, v12
	ds_bpermute_b32 v12, v22, v7
	s_and_saveexec_b64 s[4:5], s[40:41]
	s_cbranch_execz .LBB0_590
	s_waitcnt lgkmcnt(0)
	v_add_f32_e32 v2, v7, v12
	v_lshlrev_b32_e32 v4, 2, v6
	global_atomic_add_f32 v4, v2, s[44:45]
	s_branch .LBB0_590
